# P1 schedule: per-round rotation of workgroup-to-unit assignment (multiples of 8) to even out conv-tile epilogues
# baseline (speedup 1.0000x reference)
;     __host__ __device__ bool next(int i, Unit& u) const {
;         const long L = (long)i * G + c; if (L >= nwg) return false;
;         int wgid = (int)L; { const int q = nwg / NXCD, r = nwg % NXCD, xcd = wgid % NXCD, off = wgid / NXCD; wgid = (xcd < r ? xcd * (q + 1) : r * (q + 1) + (xcd - r) * q) + off; }
;         const int nig = WGM * nN, gid = wgid / nig, fm = gid * WGM, gsz = (nM - fm) < WGM ? (nM - fm) : WGM;
;         u.pm = fm + ((wgid % nig) % gsz); u.pn = (wgid % nig) / gsz; return true;
; template <class Epi, class Sched, bool ALIGN_EPI = true>
; __device__ __forceinline__ void gemm_phase(LAS unsigned char* lds, const Gemm g, const Sched& S, const Epi& E) {
;     ...
;         const bool has_next = S.next(ui + 1, nxt);
;         const char* nA = has_next ? (const char*)g.A + ((long)nxt.pm * g.mstride + g.moff) * (long)(g.lda * 2) : cA; const char* nB = has_next ? (const char*)g.Bt + (size_t)nxt.pn * tsB : cB;
.LBB0_125:
	s_add_i32 s29, s29, 1
	s_mul_i32 s0, s29, s45
	s_mul_hi_u32 s1, s29, s46
	s_add_i32 s1, s1, s0
	s_mul_i32 s0, s29, s46
	s_add_u32 s0, s0, s88
	s_addc_u32 s1, s1, s47
	s_cmp_gt_u32 s29, 10
	s_cbranch_scc1 .Lp1rot_skip
	s_mul_i32 s98, s29, 5
	s_mov_b32 s100, 0x9eeade0
	s_mov_b32 s101, 0x60924
	s_lshr_b64 s[100:101], s[100:101], s98
	s_and_b32 s100, s100, 31
	s_lshl_b32 s100, s100, 3
	s_add_i32 s99, s88, s100
	s_and_b32 s99, s99, 0xff
	s_sub_i32 s0, s0, s88
	s_add_i32 s0, s0, s99
.Lp1rot_skip:
	v_cmp_gt_i64_e32 vcc, s[0:1], v[144:145]
	v_cmp_lt_i64_e64 s[4:5], s[0:1], v[142:143]
	s_cbranch_vccnz .LBB0_131
	s_ashr_i32 s1, s0, 31
	s_lshr_b32 s1, s1, 29
	s_add_i32 s3, s0, s1
	s_and_b32 s1, s3, -8
	s_sub_i32 s16, s0, s1
	s_cmp_gt_i32 s16, 4
	s_mov_b64 s[0:1], -1
	s_cbranch_scc0 .LBB0_128
	s_mul_i32 s0, s16, 0x178
	s_or_b32 s17, s0, 5
	s_mov_b64 s[0:1], 0
